# v16 + nt on the LDS-DMA staging loads of the S5 output GEMM (row tiles read once)
# speedup vs baseline: 1.0001x; 1.0001x over previous
.LBB0_1359:
	v_readlane_b32 s16, v253, 28
	s_add_u32 s4, s8, 0x20080
	v_mov_b32_e32 v137, v203
	v_readlane_b32 s17, v253, 29
	s_addc_u32 s5, s9, 0
	s_add_i32 m0, s25, 0x18000
	v_lshl_add_u64 v[2:3], v[2:3], 0, s[80:81]
	v_lshl_add_u64 v[14:15], s[16:17], 0, v[136:137]
	v_mov_b32_e32 v133, v203
	s_waitcnt vmcnt(2)
	s_barrier
	global_load_lds_dwordx4 v[2:3], off nt
	v_lshl_add_u64 v[2:3], v[4:5], 0, s[80:81]
	s_add_i32 m0, s25, 0x1a000
	s_add_i32 s29, s25, 0x8000
	v_lshl_add_u64 v[16:17], s[16:17], 0, v[132:133]
	global_load_lds_dwordx4 v[2:3], off nt
	v_lshl_add_u64 v[2:3], v[14:15], 0, s[80:81]
	s_mov_b32 m0, s29
	s_add_i32 s30, s25, 0xa000
	global_load_lds_dwordx4 v[2:3], off nt
	v_lshl_add_u64 v[2:3], v[16:17], 0, s[80:81]
	s_mov_b32 m0, s30
	v_lshrrev_b32_e32 v18, 1, v12
	global_load_lds_dwordx4 v[2:3], off nt
	s_add_i32 m0, s25, 0x1c000
	v_lshl_add_u64 v[2:3], s[4:5], 0, v[134:135]
	global_load_lds_dwordx4 v[2:3], off nt
	v_lshl_add_u64 v[2:3], s[4:5], 0, v[130:131]
	s_add_i32 m0, s25, 0x1e000
	s_lshl_b32 s0, s0, 5
	global_load_lds_dwordx4 v[2:3], off nt
	v_and_b32_e32 v19, 24, v18
	s_and_b32 s0, s0, 0x60
	v_or_b32_e32 v3, s0, v19
	v_lshrrev_b32_e32 v144, 4, v3
	v_lshlrev_b32_e32 v3, 13, v10
	v_and_b32_e32 v3, 0xffffc000, v3
	v_lshl_add_u32 v3, v9, 10, v3
	v_and_b32_e32 v4, 1, v10
	v_lshl_or_b32 v3, v4, 6, v3
	v_and_b32_e32 v13, 15, v12
	v_lshlrev_b32_e32 v20, 1, v19
	v_lshlrev_b32_e32 v12, 2, v12
	v_lshl_add_u32 v138, v11, 1, v3
	v_lshlrev_b32_e32 v3, 13, v6
	v_lshl_or_b32 v142, s1, 6, v13
	v_lshl_or_b32 v13, v13, 6, v20
	s_lshl_b32 s1, s1, 13
	v_and_b32_e32 v12, 32, v12
	v_and_b32_e32 v3, 0xffffc000, v3
	v_bitop3_b32 v20, v13, s1, v12 bitop3:0xde
	s_lshl_b32 s1, s0, 7
	s_waitcnt vmcnt(6)
	v_lshl_add_u32 v3, v7, 10, v3
	v_and_b32_e32 v4, 1, v6
	v_bitop3_b32 v143, v13, s1, v12 bitop3:0xde
	s_cmpk_lt_u32 s2, 0x100
	v_and_b32_e32 v2, 8, v18
	v_lshl_or_b32 v3, v4, 6, v3
	v_readlane_b32 s0, v253, 36
	s_cselect_b64 s[14:15], -1, 0
	v_or_b32_e32 v145, 8, v144
	v_mov_b32_e32 v139, v203
	v_lshl_add_u32 v140, v8, 1, v3
	v_mov_b32_e32 v141, v203
	s_mov_b32 s31, 0
	v_add_u32_e32 v146, 0, v20
	v_lshlrev_b32_e32 v202, 1, v2
	s_mov_b32 s35, s0
	s_mov_b32 s34, s56
	s_barrier
	v_readlane_b32 s1, v253, 37
	s_branch .LBB0_1362

.LBB0_1363:
	s_add_u32 s0, s20, 0xfffe0080
	s_addc_u32 s1, s21, -1
	s_add_i32 s33, 0, 0x10000
	s_cmp_eq_u32 s59, 4
	s_cselect_b32 s5, s38, s1
	s_cselect_b32 s4, s39, s0
	v_add_u32_e32 v147, s33, v143
	s_cselect_b32 s3, s40, s58
	s_cselect_b32 s2, s41, s49
	s_add_i32 s55, 0, 0x14000
	ds_read_b128 v[148:151], v147
	ds_read_b128 v[152:155], v147 offset:1024
	ds_read_b128 v[156:159], v147 offset:2048
	ds_read_b128 v[160:163], v147 offset:3072
	v_add_u32_e32 v147, s55, v143
	ds_read_b128 v[164:167], v147
	ds_read_b128 v[168:171], v147 offset:1024
	ds_read_b128 v[172:175], v147 offset:2048
	ds_read_b128 v[176:179], v147 offset:3072
	v_lshl_add_u64 v[200:201], s[20:21], 0, v[138:139]
	s_add_i32 m0, s25, 0xc000
	ds_read_b128 v[180:183], v146
	ds_read_b128 v[184:187], v146 offset:1024
	ds_read_b128 v[188:191], v146 offset:2048
	ds_read_b128 v[192:195], v146 offset:3072
	ds_read_b128 v[196:199], v146 offset:4096
	ds_read_b128 v[208:211], v146 offset:5120
	ds_read_b128 v[212:215], v146 offset:6144
	ds_read_b128 v[216:219], v146 offset:7168
	global_load_lds_dwordx4 v[200:201], off nt
	v_lshl_add_u64 v[200:201], s[20:21], 0, v[140:141]
	s_add_i32 m0, s25, 0xe000
	s_nop 0
	global_load_lds_dwordx4 v[200:201], off nt
	s_waitcnt vmcnt(8)
	s_waitcnt lgkmcnt(0)
	s_barrier
	s_setprio 1
	s_waitcnt lgkmcnt(0)
	v_mfma_f32_16x16x32_bf16 v[126:129], v[148:151], v[180:183], v[126:129]
	v_mfma_f32_16x16x32_bf16 v[122:125], v[156:159], v[180:183], v[122:125]
	v_mfma_f32_16x16x32_bf16 v[110:113], v[148:151], v[188:191], v[110:113]
	v_mfma_f32_16x16x32_bf16 v[106:109], v[156:159], v[188:191], v[106:109]
	v_mfma_f32_16x16x32_bf16 v[94:97], v[148:151], v[196:199], v[94:97]
	v_mfma_f32_16x16x32_bf16 v[90:93], v[156:159], v[196:199], v[90:93]
	v_mfma_f32_16x16x32_bf16 v[78:81], v[148:151], v[212:215], v[78:81]
	v_mfma_f32_16x16x32_bf16 v[74:77], v[156:159], v[212:215], v[74:77]
	v_mfma_f32_16x16x32_bf16 v[126:129], v[152:155], v[184:187], v[126:129]
	v_mfma_f32_16x16x32_bf16 v[122:125], v[160:163], v[184:187], v[122:125]
	v_mfma_f32_16x16x32_bf16 v[110:113], v[152:155], v[192:195], v[110:113]
	v_mfma_f32_16x16x32_bf16 v[106:109], v[160:163], v[192:195], v[106:109]
	v_mfma_f32_16x16x32_bf16 v[94:97], v[152:155], v[208:211], v[94:97]
	v_mfma_f32_16x16x32_bf16 v[90:93], v[160:163], v[208:211], v[90:93]
	v_mfma_f32_16x16x32_bf16 v[78:81], v[152:155], v[216:219], v[78:81]
	v_mfma_f32_16x16x32_bf16 v[74:77], v[160:163], v[216:219], v[74:77]
	s_setprio 0
	s_setprio 1
	v_mfma_f32_16x16x32_bf16 v[118:121], v[164:167], v[180:183], v[118:121]
	v_mfma_f32_16x16x32_bf16 v[114:117], v[172:175], v[180:183], v[114:117]
	v_mfma_f32_16x16x32_bf16 v[102:105], v[164:167], v[188:191], v[102:105]
	v_mfma_f32_16x16x32_bf16 v[98:101], v[172:175], v[188:191], v[98:101]
	v_mfma_f32_16x16x32_bf16 v[86:89], v[164:167], v[196:199], v[86:89]
	v_mfma_f32_16x16x32_bf16 v[82:85], v[172:175], v[196:199], v[82:85]
	v_mfma_f32_16x16x32_bf16 v[70:73], v[164:167], v[212:215], v[70:73]
	v_mfma_f32_16x16x32_bf16 v[66:69], v[172:175], v[212:215], v[66:69]
	v_mfma_f32_16x16x32_bf16 v[118:121], v[168:171], v[184:187], v[118:121]
	v_mfma_f32_16x16x32_bf16 v[114:117], v[176:179], v[184:187], v[114:117]
	v_mfma_f32_16x16x32_bf16 v[102:105], v[168:171], v[192:195], v[102:105]
	v_mfma_f32_16x16x32_bf16 v[98:101], v[176:179], v[192:195], v[98:101]
	v_mfma_f32_16x16x32_bf16 v[86:89], v[168:171], v[208:211], v[86:89]
	v_mfma_f32_16x16x32_bf16 v[82:85], v[176:179], v[208:211], v[82:85]
	v_mfma_f32_16x16x32_bf16 v[70:73], v[168:171], v[216:219], v[70:73]
	v_mfma_f32_16x16x32_bf16 v[66:69], v[176:179], v[216:219], v[66:69]
	s_setprio 0
	s_barrier
	s_add_i32 s0, s33, s24
	v_lshl_add_u64 v[200:201], s[2:3], 0, v[134:135]
	s_mov_b32 m0, s0
	ds_read_b128 v[180:183], v146 offset:16384
	ds_read_b128 v[184:187], v146 offset:17408
	ds_read_b128 v[188:191], v146 offset:18432
	ds_read_b128 v[192:195], v146 offset:19456
	ds_read_b128 v[196:199], v146 offset:20480
	ds_read_b128 v[208:211], v146 offset:21504
	ds_read_b128 v[212:215], v146 offset:22528
	ds_read_b128 v[216:219], v146 offset:23552
	global_load_lds_dwordx4 v[200:201], off nt
	s_add_i32 m0, s0, 0x2000
	s_add_u32 s0, s2, 0x20000
	v_lshl_add_u64 v[204:205], s[2:3], 0, v[130:131]
	s_addc_u32 s1, s3, 0
	s_add_i32 s33, s55, s24
	global_load_lds_dwordx4 v[204:205], off nt
	v_lshl_add_u64 v[206:207], s[0:1], 0, v[134:135]
	s_mov_b32 m0, s33
	v_lshl_add_u64 v[220:221], s[4:5], 0, v[132:133]
	global_load_lds_dwordx4 v[206:207], off nt
	v_lshl_add_u64 v[206:207], s[0:1], 0, v[130:131]
	s_add_i32 m0, s33, 0x2000
	s_nop 0
	global_load_lds_dwordx4 v[206:207], off nt
	v_lshl_add_u64 v[206:207], s[4:5], 0, v[136:137]
	s_mov_b32 m0, s25
	s_nop 0
	global_load_lds_dwordx4 v[206:207], off nt
	s_mov_b32 m0, s26
	s_nop 0
	global_load_lds_dwordx4 v[220:221], off nt
	s_waitcnt vmcnt(8)
	s_waitcnt lgkmcnt(0)
	s_barrier
	s_setprio 1
	s_waitcnt lgkmcnt(0)
	v_mfma_f32_16x16x32_bf16 v[62:65], v[148:151], v[180:183], v[62:65]
	v_mfma_f32_16x16x32_bf16 v[58:61], v[156:159], v[180:183], v[58:61]
	v_mfma_f32_16x16x32_bf16 v[46:49], v[148:151], v[188:191], v[46:49]
	v_mfma_f32_16x16x32_bf16 v[42:45], v[156:159], v[188:191], v[42:45]
	v_mfma_f32_16x16x32_bf16 v[30:33], v[148:151], v[196:199], v[30:33]
	v_mfma_f32_16x16x32_bf16 v[26:29], v[156:159], v[196:199], v[26:29]
	v_mfma_f32_16x16x32_bf16 v[14:17], v[148:151], v[212:215], v[14:17]
	v_mfma_f32_16x16x32_bf16 v[10:13], v[156:159], v[212:215], v[10:13]
	v_mfma_f32_16x16x32_bf16 v[62:65], v[152:155], v[184:187], v[62:65]
	v_mfma_f32_16x16x32_bf16 v[58:61], v[160:163], v[184:187], v[58:61]
	v_mfma_f32_16x16x32_bf16 v[46:49], v[152:155], v[192:195], v[46:49]
	v_mfma_f32_16x16x32_bf16 v[42:45], v[160:163], v[192:195], v[42:45]
	v_mfma_f32_16x16x32_bf16 v[30:33], v[152:155], v[208:211], v[30:33]
	v_mfma_f32_16x16x32_bf16 v[26:29], v[160:163], v[208:211], v[26:29]
	v_mfma_f32_16x16x32_bf16 v[14:17], v[152:155], v[216:219], v[14:17]
	v_mfma_f32_16x16x32_bf16 v[10:13], v[160:163], v[216:219], v[10:13]
	s_setprio 0
	s_setprio 1
	v_mfma_f32_16x16x32_bf16 v[54:57], v[164:167], v[180:183], v[54:57]
	v_mfma_f32_16x16x32_bf16 v[50:53], v[172:175], v[180:183], v[50:53]
	v_mfma_f32_16x16x32_bf16 v[38:41], v[164:167], v[188:191], v[38:41]
	v_mfma_f32_16x16x32_bf16 v[34:37], v[172:175], v[188:191], v[34:37]
	v_mfma_f32_16x16x32_bf16 v[22:25], v[164:167], v[196:199], v[22:25]
	v_mfma_f32_16x16x32_bf16 v[18:21], v[172:175], v[196:199], v[18:21]
	v_mfma_f32_16x16x32_bf16 v[6:9], v[164:167], v[212:215], v[6:9]
	v_mfma_f32_16x16x32_bf16 v[2:5], v[172:175], v[212:215], v[2:5]
	v_mfma_f32_16x16x32_bf16 v[54:57], v[168:171], v[184:187], v[54:57]
	v_mfma_f32_16x16x32_bf16 v[50:53], v[176:179], v[184:187], v[50:53]
	v_mfma_f32_16x16x32_bf16 v[38:41], v[168:171], v[192:195], v[38:41]
	v_mfma_f32_16x16x32_bf16 v[34:37], v[176:179], v[192:195], v[34:37]
	v_mfma_f32_16x16x32_bf16 v[22:25], v[168:171], v[208:211], v[22:25]
	v_mfma_f32_16x16x32_bf16 v[18:21], v[176:179], v[208:211], v[18:21]
	v_mfma_f32_16x16x32_bf16 v[6:9], v[168:171], v[216:219], v[6:9]
	v_mfma_f32_16x16x32_bf16 v[2:5], v[176:179], v[216:219], v[2:5]
	s_setprio 0
	s_barrier
	s_add_i32 s33, 0, 0x18000
	v_add_u32_e32 v147, s33, v143
	s_add_i32 s55, 0, 0x1c000
	ds_read_b128 v[148:151], v147
	ds_read_b128 v[152:155], v147 offset:1024
	ds_read_b128 v[156:159], v147 offset:2048
	ds_read_b128 v[160:163], v147 offset:3072
	v_add_u32_e32 v147, s55, v143
	ds_read_b128 v[164:167], v147
	ds_read_b128 v[168:171], v147 offset:1024
	ds_read_b128 v[172:175], v147 offset:2048
	ds_read_b128 v[176:179], v147 offset:3072
	s_add_u32 s0, s4, 0x20000
	s_addc_u32 s1, s5, 0
	s_mov_b32 m0, s27
	v_lshl_add_u64 v[222:223], s[0:1], 0, v[136:137]
	ds_read_b128 v[180:183], v146 offset:32768
	ds_read_b128 v[184:187], v146 offset:33792
	ds_read_b128 v[188:191], v146 offset:34816
	ds_read_b128 v[192:195], v146 offset:35840
	ds_read_b128 v[196:199], v146 offset:36864
	ds_read_b128 v[208:211], v146 offset:37888
	ds_read_b128 v[212:215], v146 offset:38912
	ds_read_b128 v[216:219], v146 offset:39936
	global_load_lds_dwordx4 v[222:223], off nt
	v_lshl_add_u64 v[222:223], s[0:1], 0, v[132:133]
	s_mov_b32 m0, s28
	s_nop 0
	global_load_lds_dwordx4 v[222:223], off nt
	s_waitcnt vmcnt(8)
	s_waitcnt lgkmcnt(0)
	s_barrier
	s_setprio 1
	s_waitcnt lgkmcnt(0)
	v_mfma_f32_16x16x32_bf16 v[126:129], v[148:151], v[180:183], v[126:129]
	v_mfma_f32_16x16x32_bf16 v[122:125], v[156:159], v[180:183], v[122:125]
	v_mfma_f32_16x16x32_bf16 v[110:113], v[148:151], v[188:191], v[110:113]
	v_mfma_f32_16x16x32_bf16 v[106:109], v[156:159], v[188:191], v[106:109]
	v_mfma_f32_16x16x32_bf16 v[94:97], v[148:151], v[196:199], v[94:97]
	v_mfma_f32_16x16x32_bf16 v[90:93], v[156:159], v[196:199], v[90:93]
	v_mfma_f32_16x16x32_bf16 v[78:81], v[148:151], v[212:215], v[78:81]
	v_mfma_f32_16x16x32_bf16 v[74:77], v[156:159], v[212:215], v[74:77]
	v_mfma_f32_16x16x32_bf16 v[126:129], v[152:155], v[184:187], v[126:129]
	v_mfma_f32_16x16x32_bf16 v[122:125], v[160:163], v[184:187], v[122:125]
	v_mfma_f32_16x16x32_bf16 v[110:113], v[152:155], v[192:195], v[110:113]
	v_mfma_f32_16x16x32_bf16 v[106:109], v[160:163], v[192:195], v[106:109]
	v_mfma_f32_16x16x32_bf16 v[94:97], v[152:155], v[208:211], v[94:97]
	v_mfma_f32_16x16x32_bf16 v[90:93], v[160:163], v[208:211], v[90:93]
	v_mfma_f32_16x16x32_bf16 v[78:81], v[152:155], v[216:219], v[78:81]
	v_mfma_f32_16x16x32_bf16 v[74:77], v[160:163], v[216:219], v[74:77]
	s_setprio 0
	s_setprio 1
	v_mfma_f32_16x16x32_bf16 v[118:121], v[164:167], v[180:183], v[118:121]
	v_mfma_f32_16x16x32_bf16 v[114:117], v[172:175], v[180:183], v[114:117]
	v_mfma_f32_16x16x32_bf16 v[102:105], v[164:167], v[188:191], v[102:105]
	v_mfma_f32_16x16x32_bf16 v[98:101], v[172:175], v[188:191], v[98:101]
	v_mfma_f32_16x16x32_bf16 v[86:89], v[164:167], v[196:199], v[86:89]
	v_mfma_f32_16x16x32_bf16 v[82:85], v[172:175], v[196:199], v[82:85]
	v_mfma_f32_16x16x32_bf16 v[70:73], v[164:167], v[212:215], v[70:73]
	v_mfma_f32_16x16x32_bf16 v[66:69], v[172:175], v[212:215], v[66:69]
	v_mfma_f32_16x16x32_bf16 v[118:121], v[168:171], v[184:187], v[118:121]
	v_mfma_f32_16x16x32_bf16 v[114:117], v[176:179], v[184:187], v[114:117]
	v_mfma_f32_16x16x32_bf16 v[102:105], v[168:171], v[192:195], v[102:105]
	v_mfma_f32_16x16x32_bf16 v[98:101], v[176:179], v[192:195], v[98:101]
	v_mfma_f32_16x16x32_bf16 v[86:89], v[168:171], v[208:211], v[86:89]
	v_mfma_f32_16x16x32_bf16 v[82:85], v[176:179], v[208:211], v[82:85]
	v_mfma_f32_16x16x32_bf16 v[70:73], v[168:171], v[216:219], v[70:73]
	v_mfma_f32_16x16x32_bf16 v[66:69], v[176:179], v[216:219], v[66:69]
	s_setprio 0
	s_barrier
	s_add_i32 s0, s33, s24
	v_lshl_add_u64 v[200:201], v[200:201], 0, s[80:81]
	s_mov_b32 m0, s0
	ds_read_b128 v[180:183], v146 offset:49152
	ds_read_b128 v[184:187], v146 offset:50176
	ds_read_b128 v[188:191], v146 offset:51200
	ds_read_b128 v[192:195], v146 offset:52224
	ds_read_b128 v[196:199], v146 offset:53248
	ds_read_b128 v[208:211], v146 offset:54272
	ds_read_b128 v[212:215], v146 offset:55296
	ds_read_b128 v[216:219], v146 offset:56320
	global_load_lds_dwordx4 v[200:201], off nt
	s_add_i32 m0, s0, 0x2000
	s_add_u32 s0, s2, 0x20080
	v_lshl_add_u64 v[200:201], v[204:205], 0, s[80:81]
	s_addc_u32 s1, s3, 0
	s_add_i32 s2, s55, s24
	global_load_lds_dwordx4 v[200:201], off nt
	v_lshl_add_u64 v[200:201], s[0:1], 0, v[134:135]
	s_mov_b32 m0, s2
	s_nop 0
	global_load_lds_dwordx4 v[200:201], off nt
	v_lshl_add_u64 v[200:201], s[0:1], 0, v[130:131]
	s_add_i32 m0, s2, 0x2000
	s_nop 0
	global_load_lds_dwordx4 v[200:201], off nt
	v_lshl_add_u64 v[200:201], v[206:207], 0, s[80:81]
	s_mov_b32 m0, s29
	s_nop 0
	global_load_lds_dwordx4 v[200:201], off nt
	v_lshl_add_u64 v[200:201], v[220:221], 0, s[80:81]
	s_mov_b32 m0, s30
	s_nop 0
	global_load_lds_dwordx4 v[200:201], off nt
	s_waitcnt vmcnt(8)
	s_waitcnt lgkmcnt(0)
	s_barrier
	s_setprio 1
	s_waitcnt lgkmcnt(0)
	v_mfma_f32_16x16x32_bf16 v[62:65], v[148:151], v[180:183], v[62:65]
	v_mfma_f32_16x16x32_bf16 v[58:61], v[156:159], v[180:183], v[58:61]
	v_mfma_f32_16x16x32_bf16 v[46:49], v[148:151], v[188:191], v[46:49]
	v_mfma_f32_16x16x32_bf16 v[42:45], v[156:159], v[188:191], v[42:45]
	v_mfma_f32_16x16x32_bf16 v[30:33], v[148:151], v[196:199], v[30:33]
	v_mfma_f32_16x16x32_bf16 v[26:29], v[156:159], v[196:199], v[26:29]
	v_mfma_f32_16x16x32_bf16 v[14:17], v[148:151], v[212:215], v[14:17]
	v_mfma_f32_16x16x32_bf16 v[10:13], v[156:159], v[212:215], v[10:13]
	v_mfma_f32_16x16x32_bf16 v[62:65], v[152:155], v[184:187], v[62:65]
	v_mfma_f32_16x16x32_bf16 v[58:61], v[160:163], v[184:187], v[58:61]
	v_mfma_f32_16x16x32_bf16 v[46:49], v[152:155], v[192:195], v[46:49]
	v_mfma_f32_16x16x32_bf16 v[42:45], v[160:163], v[192:195], v[42:45]
	v_mfma_f32_16x16x32_bf16 v[30:33], v[152:155], v[208:211], v[30:33]
	v_mfma_f32_16x16x32_bf16 v[26:29], v[160:163], v[208:211], v[26:29]
	v_mfma_f32_16x16x32_bf16 v[14:17], v[152:155], v[216:219], v[14:17]
	v_mfma_f32_16x16x32_bf16 v[10:13], v[160:163], v[216:219], v[10:13]
	s_setprio 0
	s_setprio 1
	v_mfma_f32_16x16x32_bf16 v[54:57], v[164:167], v[180:183], v[54:57]
	v_mfma_f32_16x16x32_bf16 v[50:53], v[172:175], v[180:183], v[50:53]
	v_mfma_f32_16x16x32_bf16 v[38:41], v[164:167], v[188:191], v[38:41]
	v_mfma_f32_16x16x32_bf16 v[34:37], v[172:175], v[188:191], v[34:37]
	v_mfma_f32_16x16x32_bf16 v[22:25], v[164:167], v[196:199], v[22:25]
	v_mfma_f32_16x16x32_bf16 v[18:21], v[172:175], v[196:199], v[18:21]
	v_mfma_f32_16x16x32_bf16 v[6:9], v[164:167], v[212:215], v[6:9]
	v_mfma_f32_16x16x32_bf16 v[2:5], v[172:175], v[212:215], v[2:5]
	v_mfma_f32_16x16x32_bf16 v[54:57], v[168:171], v[184:187], v[54:57]
	v_mfma_f32_16x16x32_bf16 v[50:53], v[176:179], v[184:187], v[50:53]
	v_mfma_f32_16x16x32_bf16 v[38:41], v[168:171], v[192:195], v[38:41]
	v_mfma_f32_16x16x32_bf16 v[34:37], v[176:179], v[192:195], v[34:37]
	v_mfma_f32_16x16x32_bf16 v[22:25], v[168:171], v[208:211], v[22:25]
	v_mfma_f32_16x16x32_bf16 v[18:21], v[176:179], v[208:211], v[18:21]
	v_mfma_f32_16x16x32_bf16 v[6:9], v[168:171], v[216:219], v[6:9]
	v_mfma_f32_16x16x32_bf16 v[2:5], v[176:179], v[216:219], v[2:5]
	s_setprio 0
	s_barrier
	s_add_i32 s59, s59, 2
	s_add_u32 s20, s20, 0x100
	s_addc_u32 s21, s21, 0
	s_add_u32 s49, s49, 0x100
	s_addc_u32 s58, s58, 0
	s_cmp_gt_u32 s59, 5
	s_cbranch_scc0 .LBB0_1363
	s_and_b64 vcc, exec, s[14:15]
	s_cbranch_vccz .LBB0_1366
	s_barrier
